# w8 + lambda parameter loads (4 dwords per lane) issued at the start of the layer-1 in-projection phase instead of at the differential-attention phase start behind a vmcnt(0)
# speedup vs baseline: 1.0014x; 1.0005x over previous
.Lxb_done_6:
	s_waitcnt vmcnt(0)
	s_nop 0
.LBB0_1006:
	s_or_b64 exec, exec, s[0:1]
.LBB0_1007:
	s_waitcnt vmcnt(11) lgkmcnt(0)
	v_mov_b32_e32 v0, v206
	s_mov_b32 s28, s77
	s_mov_b32 s29, s78
	s_waitcnt vmcnt(9)
	v_mov_b32_e32 v9, v206
	s_barrier
	v_and_b32_e32 v231, 63, v206
	v_lshlrev_b32_e32 v231, 2, v231
	global_load_dword v232, v231, s[56:57]
	global_load_dword v233, v231, s[58:59]
	global_load_dword v234, v231, s[60:61]
	global_load_dword v235, v231, s[62:63]
	s_cmpk_gt_i32 s28, 0x2ff
	v_readfirstlane_b32 s1, v9
	s_cbranch_scc1 .LBB0_1023
	v_lshlrev_b32_e32 v0, 4, v9
	v_add_u32_e32 v1, 0x2000, v0
	v_ashrrev_i32_e32 v2, 31, v1
	v_lshrrev_b32_e32 v2, 22, v2
	v_add_u32_e32 v2, v1, v2
	v_ashrrev_i32_e32 v8, 10, v2
	v_mul_i32_i24_e32 v2, 0x400, v8
	v_sub_u32_e32 v1, v1, v2
	v_lshrrev_b32_e32 v2, 4, v1
	v_bitop3_b32 v1, v2, v1, 32 bitop3:0x6c
	v_ashrrev_i32_e32 v2, 31, v1
	v_lshrrev_b32_e32 v2, 26, v2
	v_add_u32_e32 v2, v1, v2
	v_lshlrev_b32_e32 v3, 3, v8
	v_ashrrev_i32_e32 v10, 6, v2
	v_and_b32_e32 v3, -16, v3
	v_add_u32_e32 v3, v10, v3
	v_and_b32_e32 v4, 3, v10
	s_mov_b32 s0, 0x1fffe0
	v_lshrrev_b32_e32 v5, 2, v3
	v_lshlrev_b32_e32 v6, 1, v3
	v_and_b32_e32 v2, 0xc0, v2
	v_and_or_b32 v4, v3, s0, v4
	v_and_b32_e32 v5, 4, v5
	v_and_b32_e32 v6, 24, v6
	v_sub_u32_e32 v1, v1, v2
	v_mov_b32_e32 v2, 1
	v_or3_b32 v4, v4, v5, v6
	v_lshlrev_b32_e32 v5, 5, v8
	v_ashrrev_i16_sdwa v1, v2, sext(v1) dst_sel:DWORD dst_unused:UNUSED_PAD src0_sel:DWORD src1_sel:BYTE_0
	v_and_b32_e32 v5, 32, v5
	v_bfe_i32 v11, v1, 0, 16
	v_add_lshl_u32 v1, v5, v11, 1
	v_lshl_add_u32 v128, v4, 11, v1
	v_lshl_add_u32 v130, v3, 11, v1
	v_bfe_i32 v1, v9, 27, 1
	v_lshrrev_b32_e32 v1, 22, v1
	v_add_u32_e32 v1, v0, v1
	v_and_b32_e32 v1, 0xfffffc00, v1
	v_sub_u32_e32 v0, v0, v1
	v_lshrrev_b32_e32 v1, 4, v0
	v_ashrrev_i32_e32 v3, 31, v9
	v_bitop3_b32 v0, v1, v0, 32 bitop3:0x6c
	v_lshrrev_b32_e32 v3, 26, v3
	v_ashrrev_i32_e32 v1, 31, v0
	v_add_u32_e32 v3, v9, v3
	v_lshrrev_b32_e32 v1, 26, v1
	s_waitcnt vmcnt(8)
	v_ashrrev_i32_e32 v13, 6, v3
	v_add_u32_e32 v1, v0, v1
	v_lshlrev_b32_e32 v3, 3, v13
	s_add_u32 s30, s74, 0x1a00000
	v_ashrrev_i32_e32 v12, 6, v1
	v_and_b32_e32 v3, -16, v3
	s_addc_u32 s31, s75, 0
	v_add_u32_e32 v3, v12, v3
	v_and_b32_e32 v4, 3, v12
	s_ashr_i32 s34, s28, 31
	v_and_or_b32 v4, v3, s0, v4
	s_lshr_b32 s0, s34, 29
	s_add_i32 s0, s28, s0
	s_ashr_i32 s3, s1, 6
	s_ashr_i32 s4, s0, 3
	s_and_b32 s0, s0, -8
	s_ashr_i32 s10, s1, 8
	s_lshl_b32 s33, s3, 10
	s_sub_i32 s0, s28, s0
	s_cmp_lt_i32 s0, 0
	s_movk_i32 s35, 0x61
	s_cselect_b32 s5, s35, 0x60
	s_mul_i32 s0, s0, s5
	s_add_i32 s0, s0, s4
	s_mul_hi_i32 s4, s0, 0x2aaaaaab
	s_lshr_b32 s5, s4, 31
	s_ashr_i32 s4, s4, 4
	s_add_i32 s4, s4, s5
	s_lshl_b32 s5, s4, 3
	s_mulk_i32 s4, 0x60
	s_sub_i32 s4, s0, s4
	s_bfe_i32 s0, s4, 0x80000
	s_bfe_u32 s0, s0, 0x3000c
	s_add_i32 s8, s4, s0
	s_bfe_i32 s0, s8, 0x80000
	s_and_b32 s8, s8, 0xf8
	s_sub_i32 s4, s4, s8
	s_sext_i32_i16 s0, s0
	s_sext_i32_i8 s4, s4
	v_lshrrev_b32_e32 v5, 2, v3
	v_lshlrev_b32_e32 v6, 1, v3
	v_and_b32_e32 v1, 0xc0, v1
	s_lshr_b32 s0, s0, 3
	s_add_i32 s20, s5, s4
	v_and_b32_e32 v5, 4, v5
	v_and_b32_e32 v6, 24, v6
	v_sub_u32_e32 v0, v0, v1
	s_ashr_i32 s21, s20, 31
	s_bfe_i64 s[8:9], s[0:1], 0x100000
	v_or3_b32 v4, v4, v5, v6
	v_lshlrev_b32_e32 v5, 5, v13
	v_ashrrev_i16_sdwa v0, v2, sext(v0) dst_sel:DWORD dst_unused:UNUSED_PAD src0_sel:DWORD src1_sel:BYTE_0
	s_lshl_b64 s[4:5], s[20:21], 19
	s_lshl_b64 s[8:9], s[8:9], 19
	v_and_b32_e32 v5, 32, v5
	v_bfe_i32 v14, v0, 0, 16
	s_add_u32 s24, s30, s8
	v_add_lshl_u32 v0, v5, v14, 1
	s_addc_u32 s25, s31, s9
	s_add_i32 s21, s33, 0
	v_lshl_add_u32 v132, v4, 11, v0
	s_add_i32 m0, s21, 0x10000
	v_lshl_add_u32 v134, v3, 11, v0
	global_load_lds_dwordx4 v132, s[24:25]
	s_add_i32 m0, s21, 0x12000
	s_add_u32 s8, s24, 0x40000
	global_load_lds_dwordx4 v128, s[24:25]
	s_addc_u32 s9, s25, 0
	s_add_i32 m0, s21, 0x14000
	v_mov_b32_e32 v133, 0
	global_load_lds_dwordx4 v132, s[8:9]
	s_add_i32 m0, s21, 0x16000
	s_add_u32 s22, s82, s4
	s_addc_u32 s23, s83, s5
	s_add_i32 s36, s21, 0x2000
	global_load_lds_dwordx4 v128, s[8:9]
	s_mov_b32 m0, s21
	s_add_u32 s4, s22, 0x40000
	global_load_lds_dwordx4 v134, s[22:23]
	s_mov_b32 m0, s36
	s_addc_u32 s5, s23, 0
	s_add_i32 s37, s21, 0x4000
	global_load_lds_dwordx4 v130, s[22:23]
	s_mov_b32 m0, s37
	s_add_i32 s38, s21, 0x6000
	global_load_lds_dwordx4 v134, s[4:5]
	s_mov_b32 m0, s38
	v_mov_b32_e32 v129, v133
	global_load_lds_dwordx4 v130, s[4:5]
	v_mov_b32_e32 v135, v133
	v_mov_b32_e32 v131, v133
	s_cmp_eq_u32 s10, 1
	s_mov_b32 s39, 0
	v_lshl_add_u64 v[6:7], s[24:25], 0, v[132:133]
	v_lshl_add_u64 v[4:5], s[24:25], 0, v[128:129]
	v_lshl_add_u64 v[0:1], s[22:23], 0, v[134:135]
	s_cselect_b64 s[4:5], -1, 0
	s_cmp_lg_u32 s10, 1
	v_lshl_add_u64 v[2:3], s[22:23], 0, v[130:131]
	s_cbranch_scc1 .LBB0_1010
	s_barrier

.LBB0_1077:
	v_and_b32_e32 v0, 63, v206
	v_and_b32_e32 v186, 31, v206
	v_bfe_u32 v3, v206, 5, 1
	v_mul_u32_u24_e32 v2, 0xc00, v0
	v_lshlrev_b32_e32 v0, 3, v206
	v_and_b32_e32 v4, 24, v0
	v_mul_u32_u24_e32 v0, 0xc00, v186
	v_lshlrev_b32_e32 v188, 3, v3
	v_or_b32_e32 v6, v188, v0
	v_lshlrev_b32_e32 v0, 10, v3
	v_lshlrev_b32_e32 v5, 4, v186
	v_add3_u32 v189, 0, v0, v5
	v_lshlrev_b32_e32 v0, 1, v206
	v_lshlrev_b32_e32 v191, 2, v3
	v_bfe_u32 v5, v206, 2, 2
	v_and_b32_e32 v0, 32, v0
	v_or_b32_e32 v5, v191, v5
	v_add_u32_e32 v0, 0, v0
	v_lshlrev_b32_e32 v5, 6, v5
	s_cmpk_lg_i32 s30, 0x100
	v_add3_u32 v192, v0, v4, v5
	v_and_b32_e32 v0, 3, v206
	s_cselect_b64 s[0:1], -1, 0
	s_and_b32 s34, s31, 15
	v_mov_b32_e32 v1, 0
	v_lshlrev_b32_e32 v0, 4, v0
	s_ashr_i32 s33, s31, 4
	s_xor_b32 s35, s34, 31
	v_and_b32_e32 v3, 15, v206
	v_lshl_add_u64 v[10:11], s[74:75], 0, v[0:1]
	s_mov_b64 s[6:7], 0x5321000
	s_add_u32 s36, s74, 0x5201000
	v_bfe_u32 v190, v206, 4, 2
	v_lshlrev_b32_e32 v8, 3, v3
	v_lshl_add_u64 v[168:169], v[10:11], 0, s[6:7]
	s_mov_b64 s[6:7], 0x52c1000
	s_addc_u32 s37, s75, 0
	v_bfe_u32 v187, v206, 2, 4
	v_mul_u32_u24_e32 v193, 0x110, v186
	v_lshlrev_b32_e32 v194, 4, v3
	v_mul_u32_u24_e32 v195, 0x110, v190
	v_lshl_add_u64 v[170:171], v[10:11], 0, s[6:7]
	v_lshlrev_b32_e32 v172, 1, v2
	s_mov_b64 s[8:9], 0x800
	v_lshlrev_b32_e32 v174, 1, v4
	s_mov_b64 s[10:11], 0x80
	s_mov_b64 s[12:13], 0x60800
	s_mov_b64 s[14:15], 0x60000
	s_mov_b64 s[16:17], 0x60080
	v_lshlrev_b32_e32 v196, 1, v6
	s_mov_b64 s[18:19], 0xc0000
	s_mov_b64 s[20:21], 0xc0080
	s_mov_b64 s[22:23], 0x120000
	s_mov_b32 s38, 0x41000000
	s_movk_i32 s39, 0x400
	v_lshlrev_b32_e32 v176, 1, v8
	v_mov_b32_e32 v197, 0x60000
	v_mov_b32_e32 v198, 0xff800000
	s_mov_b32 s40, 0
	v_and_b32_e32 v0, 63, v206
	v_lshlrev_b32_e32 v0, 2, v0
	v_mov_b32_e32 v2, v232
	v_mov_b32_e32 v3, v233
	v_mov_b32_e32 v4, v234
	v_mov_b32_e32 v5, v235
	s_nop 0
	s_nop 0
	s_nop 0
	s_nop 0
	v_mbcnt_hi_u32_b32 v0, -1, v207
	v_xor_b32_e32 v6, 1, v0
	v_xor_b32_e32 v7, 2, v0
	v_xor_b32_e32 v8, 4, v0
	v_xor_b32_e32 v9, 8, v0
	v_xor_b32_e32 v10, 16, v0
	v_xor_b32_e32 v11, 32, v0
	v_lshlrev_b32_e32 v6, 2, v6
	v_lshlrev_b32_e32 v7, 2, v7
	v_lshlrev_b32_e32 v8, 2, v8
	v_lshlrev_b32_e32 v9, 2, v9
	v_lshlrev_b32_e32 v10, 2, v10
	v_lshlrev_b32_e32 v11, 2, v11
	s_waitcnt vmcnt(0)
	v_mul_f32_e32 v12, v2, v3
	v_mul_f32_e32 v13, v4, v5
	ds_bpermute_b32 v12, v6, v12
	ds_bpermute_b32 v13, v6, v13
	s_waitcnt lgkmcnt(0)
	v_fmac_f32_e32 v12, v2, v3
	v_fmac_f32_e32 v13, v4, v5
	ds_bpermute_b32 v2, v7, v12
	ds_bpermute_b32 v3, v7, v13
	s_waitcnt lgkmcnt(0)
	v_add_f32_e32 v12, v12, v2
	v_add_f32_e32 v13, v13, v3
	ds_bpermute_b32 v2, v8, v12
	ds_bpermute_b32 v3, v8, v13
	s_waitcnt lgkmcnt(0)
	v_add_f32_e32 v12, v12, v2
	v_add_f32_e32 v13, v13, v3
	ds_bpermute_b32 v2, v9, v12
	ds_bpermute_b32 v3, v9, v13
	s_waitcnt lgkmcnt(0)
	v_add_f32_e32 v12, v12, v2
	v_add_f32_e32 v13, v13, v3
	ds_bpermute_b32 v2, v10, v12
	ds_bpermute_b32 v3, v10, v13
	s_waitcnt lgkmcnt(0)
	v_add_f32_e32 v12, v12, v2
	v_add_f32_e32 v13, v13, v3
	ds_bpermute_b32 v2, v11, v12
	ds_bpermute_b32 v3, v11, v13
	s_waitcnt lgkmcnt(0)
	v_add_f32_e32 v12, v12, v2
	v_add_f32_e32 v13, v13, v3
	v_mul_f32_e32 v12, 0x3fb8aa3b, v12
	v_mul_f32_e32 v13, 0x3fb8aa3b, v13
	v_exp_f32_e32 v12, v12
	v_exp_f32_e32 v13, v13
	s_nop 0
	v_sub_f32_e32 v236, v12, v13
	v_add_f32_e32 v236, 0x3eb60549, v236
	v_mov_b32_e32 v237, v236
	s_branch .LBB0_1080
